# speedup vs baseline: 1.0405x; 1.0006x over previous
; __device__ __forceinline__ void qkt8(f32x16& p0, f32x16& p1, const char* Ks, const i32x8* qf, int r32, int hi) {
;   p0 = f32x16{}; p1 = f32x16{};
;   const char* kb = Ks + r32 * K8ROW + hi * 32;
;   i32x8 a0 = ld32B(kb), a1 = ld32B(kb + 32 * K8ROW);
;   i32x8 b0 = ld32B(kb + 64), b1 = ld32B(kb + 32 * K8ROW + 64);
;   p0 = mfma8(a0, qf[0], p0); p1 = mfma8(a1, qf[0], p1);
;   a0 = ld32B(kb + 128); a1 = ld32B(kb + 32 * K8ROW + 128);
;   p0 = mfma8(b0, qf[1], p0); p1 = mfma8(b1, qf[1], p1);
;   p0 = mfma8(a0, qf[2], p0); p1 = mfma8(a1, qf[2], p1);
; }
; __device__ __forceinline__ void pv8(f32x16* o, f32x16& lacc, const char* Vs, i32x8 pf, int r32, int hi) {
;   const char* vb = Vs + r32 * V8ROW + hi * 32;
; #pragma unroll
;   for (int d0 = 0; d0 < 4; ++d0) o[d0] = mfma8(pf, ld32B(vb + d0 * 32 * V8ROW), o[d0]);
;   const int one4 = 0x38383838;
;   lacc = mfma8(pf, i32x8{one4, one4, one4, one4, one4, one4, one4, one4}, lacc);
; }
; __device__ __forceinline__ void partialSM8(f32x16& p0, f32x16& p1, float& m_reg, float& mn, float& alpha) {
;   float pmax = p0[0];
; #pragma unroll
;   for (int r = 1; r < 16; ++r) pmax = fmaxf(pmax, p0[r]);
; #pragma unroll
;   for (int r = 0; r < 16; ++r) pmax = fmaxf(pmax, p1[r]);
;   { auto rr = __builtin_amdgcn_permlane32_swap(__float_as_uint(pmax), __float_as_uint(pmax), false, false);
;     pmax = fmaxf(__uint_as_float(rr[0]), __uint_as_float(rr[1])); }
;   if (__builtin_expect(__all(pmax - m_reg <= THR8 * 8.f * 1.4426950408889634f), 1)) { mn = m_reg; alpha = 1.f; }
;   else { mn = fmaxf(m_reg, pmax); alpha = __builtin_amdgcn_exp2f((m_reg - mn) * 0.125f); m_reg = mn; }
;   const float mn8 = (P8SHIFT + 7.f - 0.0436f) * 8.f + 0.5f - mn;
; #pragma unroll
;   for (int r = 0; r < 16; ++r) p0[r] += mn8;
; #pragma unroll
;   for (int r = 0; r < 16; ++r) p1[r] += mn8;
; }
; __device__ __forceinline__ unsigned pk4u8(float a, float b, float c, float d) {
;   unsigned w = __builtin_amdgcn_cvt_pk_u8_f32(a, 0u, 0u); w = __builtin_amdgcn_cvt_pk_u8_f32(b, 1u, w);
;   w = __builtin_amdgcn_cvt_pk_u8_f32(c, 2u, w); return __builtin_amdgcn_cvt_pk_u8_f32(d, 3u, w);
; }
; __device__ __forceinline__ void finishSM8(f32x16& p0, f32x16& p1, i32x8& pf) {
; #pragma unroll
;   for (int w = 0; w < 4; ++w) { pf[w] = (int)pk4u8(p0[4 * w], p0[4 * w + 1], p0[4 * w + 2], p0[4 * w + 3]);
.LBB0_912:
	s_mul_i32 s2, s22, 0x3400
	v_add_u32_e32 v113, s2, v214
	ds_read_b128 v[80:83], v113 offset:51200
	ds_read_b128 v[84:87], v113 offset:51216
	s_waitcnt lgkmcnt(0)
	v_mfma_scale_f32_32x32x64_f8f6f4 v[96:111], v[80:87], v[120:127], 0, v193, v193 op_sel_hi:[0,0,0]
	ds_read_b128 v[80:83], v113 offset:57856
	ds_read_b128 v[84:87], v113 offset:57872
	ds_read_b128 v[218:221], v113 offset:51264
	ds_read_b128 v[222:225], v113 offset:51280
	s_waitcnt lgkmcnt(2)
	v_mfma_scale_f32_32x32x64_f8f6f4 v[80:95], v[80:87], v[120:127], 0, v193, v193 op_sel_hi:[0,0,0]
	s_waitcnt lgkmcnt(0)
	v_mfma_scale_f32_32x32x64_f8f6f4 v[96:111], v[218:225], v[128:135], v[96:111], v193, v193 op_sel_hi:[0,0,0]
	ds_read_b128 v[218:221], v113 offset:57920
	ds_read_b128 v[222:225], v113 offset:57936
	ds_read_b128 v[226:229], v113 offset:51328
	ds_read_b128 v[230:233], v113 offset:51344
	ds_read_b128 v[234:237], v113 offset:57984
	ds_read_b128 v[238:241], v113 offset:58000
	v_cvt_pk_u8_f32 v113, v184, 0, 0
	v_cvt_pk_u8_f32 v113, v185, 1, v113
	v_cvt_pk_u8_f32 v113, v182, 2, v113
	s_waitcnt lgkmcnt(4)
	v_mfma_scale_f32_32x32x64_f8f6f4 v[80:95], v[218:225], v[128:135], v[80:95], v193, v193 op_sel_hi:[0,0,0]
	v_cvt_pk_u8_f32 v218, v183, 3, v113
	v_cvt_pk_u8_f32 v113, v198, 0, 0
	v_cvt_pk_u8_f32 v113, v199, 1, v113
	v_cvt_pk_u8_f32 v113, v196, 2, v113
	v_cvt_pk_u8_f32 v222, v197, 3, v113
	v_cvt_pk_u8_f32 v113, v178, 0, 0
	v_cvt_pk_u8_f32 v113, v179, 1, v113
	v_cvt_pk_u8_f32 v113, v174, 2, v113
	v_cvt_pk_u8_f32 v219, v175, 3, v113
	v_cvt_pk_u8_f32 v113, v194, 0, 0
	v_cvt_pk_u8_f32 v113, v195, 1, v113
	v_cvt_pk_u8_f32 v113, v190, 2, v113
	v_cvt_pk_u8_f32 v223, v191, 3, v113
	v_cvt_pk_u8_f32 v113, v172, 0, 0
	v_cvt_pk_u8_f32 v113, v173, 1, v113
	s_waitcnt lgkmcnt(2)
	v_mfma_scale_f32_32x32x64_f8f6f4 v[96:111], v[226:233], v[136:143], v[96:111], v193, v193 op_sel_hi:[0,0,0]
	v_cvt_pk_u8_f32 v113, v118, 2, v113
	v_cvt_pk_u8_f32 v220, v119, 3, v113
	v_cvt_pk_u8_f32 v113, v188, 0, 0
	v_cvt_pk_u8_f32 v113, v189, 1, v113
	v_cvt_pk_u8_f32 v113, v186, 2, v113
	v_cvt_pk_u8_f32 v224, v187, 3, v113
	v_cvt_pk_u8_f32 v113, v116, 0, 0
	v_cvt_pk_u8_f32 v113, v117, 1, v113
	v_cvt_pk_u8_f32 v113, v114, 2, v113
	v_cvt_pk_u8_f32 v221, v115, 3, v113
	v_cvt_pk_u8_f32 v113, v180, 0, 0
	v_cvt_pk_u8_f32 v113, v181, 1, v113
	v_cvt_pk_u8_f32 v113, v176, 2, v113
	v_cvt_pk_u8_f32 v225, v177, 3, v113
	s_waitcnt lgkmcnt(0)
	v_mfma_scale_f32_32x32x64_f8f6f4 v[80:95], v[234:241], v[136:143], v[80:95], v193, v193 op_sel_hi:[0,0,0]
	s_mul_i32 s2, s21, 0x2800
	s_addk_i32 s2, 0xd800
	s_cmp_lg_u32 s21, 0
	s_cselect_b32 s2, s2, 0xa000
	v_add_u32_e32 v113, s2, v217
	ds_read_b128 v[172:175], v113
	ds_read_b128 v[176:179], v113 offset:16
	v_max_f32_e32 v188, v97, v97
	v_max_f32_e32 v189, v96, v96
	v_max_f32_e32 v188, v189, v188
	v_max3_f32 v188, v188, v98, v99
	s_waitcnt lgkmcnt(0)
	v_mfma_scale_f32_32x32x64_f8f6f4 v[48:63], v[218:225], v[172:179], v[48:63], v193, v193 op_sel_hi:[0,0,0]
	ds_read_b128 v[172:175], v113 offset:2560
	ds_read_b128 v[176:179], v113 offset:2576
	s_waitcnt lgkmcnt(0)
	v_mfma_scale_f32_32x32x64_f8f6f4 v[32:47], v[218:225], v[172:179], v[32:47], v193, v193 op_sel_hi:[0,0,0]
	ds_read_b128 v[172:175], v113 offset:5120
	ds_read_b128 v[176:179], v113 offset:5136
	ds_read_b128 v[180:183], v113 offset:7680
	ds_read_b128 v[184:187], v113 offset:7696
	s_waitcnt lgkmcnt(2)
	v_mfma_scale_f32_32x32x64_f8f6f4 v[16:31], v[218:225], v[172:179], v[16:31], v193, v193 op_sel_hi:[0,0,0]
	v_max3_f32 v172, v188, v100, v101
	v_max3_f32 v172, v172, v102, v103
	v_max3_f32 v172, v172, v104, v105
	v_max3_f32 v172, v172, v106, v107
	v_max3_f32 v172, v172, v108, v109
	v_max3_f32 v172, v172, v110, v111
	v_max3_f32 v172, v172, v80, v81
	v_max3_f32 v172, v172, v82, v83
	v_max3_f32 v172, v172, v84, v85
	v_max3_f32 v172, v172, v86, v87
	v_max3_f32 v172, v172, v88, v89
	v_max3_f32 v172, v172, v90, v91
	v_max3_f32 v172, v172, v92, v93
	v_max3_f32 v172, v172, v94, v95
	v_mov_b32_e32 v173, v172
	s_waitcnt lgkmcnt(0)
	v_mfma_scale_f32_32x32x64_f8f6f4 v[0:15], v[218:225], v[180:187], v[0:15], v193, v193 op_sel_hi:[0,0,0]
	v_permlane32_swap_b32_e32 v172, v173
	v_max_f32_e32 v172, v172, v173
	v_sub_f32_e32 v173, v172, v216
	v_cmp_ge_f32_e32 vcc, s61, v173
	v_mfma_scale_f32_16x16x128_f8f6f4 v[64:67], v[218:225], v[244:251], v[64:67], v193, v193 op_sel_hi:[0,0,0]
	s_cmp_eq_u64 vcc, exec
	s_cselect_b64 s[10:11], -1, 0
	s_cbranch_scc1 .LBB0_916
	v_max_f32_e32 v172, v216, v172
	v_sub_f32_e32 v174, v216, v172
	v_mul_f32_e32 v174, 0x3e000000, v174
	v_exp_f32_e32 v174, v174
	s_nop 0
	v_mov_b32_e32 v173, v174
	v_cmp_gt_f32_e32 vcc, 1.0, v173
	s_cbranch_vccz .LBB0_916
	s_and_saveexec_b64 s[16:17], s[8:9]
	ds_write_b32 v215, v173 offset:128
	s_or_b64 exec, exec, s[16:17]
	s_waitcnt lgkmcnt(0)
	v_add_u32_e32 v113, v159, v213
	ds_read_b128 v[114:117], v113 offset:224
	ds_read_b128 v[174:177], v113 offset:192
	ds_read_b128 v[178:181], v113 offset:160
	ds_read_b128 v[182:185], v113 offset:128
	s_waitcnt lgkmcnt(3)
	v_pk_mul_f32 v[60:61], v[60:61], v[114:115]
	s_waitcnt lgkmcnt(2)
	v_pk_mul_f32 v[56:57], v[56:57], v[174:175]
	s_waitcnt lgkmcnt(1)
	v_pk_mul_f32 v[52:53], v[52:53], v[178:179]
	v_pk_mul_f32 v[62:63], v[62:63], v[116:117]
	v_pk_mul_f32 v[58:59], v[58:59], v[176:177]
	v_pk_mul_f32 v[54:55], v[54:55], v[180:181]
	s_waitcnt lgkmcnt(0)
	v_pk_mul_f32 v[50:51], v[50:51], v[184:185]
	v_pk_mul_f32 v[48:49], v[48:49], v[182:183]
	v_pk_mul_f32 v[44:45], v[44:45], v[114:115]
	v_pk_mul_f32 v[40:41], v[40:41], v[174:175]
	v_pk_mul_f32 v[36:37], v[36:37], v[178:179]
	v_pk_mul_f32 v[46:47], v[46:47], v[116:117]
	v_pk_mul_f32 v[42:43], v[42:43], v[176:177]
	v_pk_mul_f32 v[38:39], v[38:39], v[180:181]
	v_pk_mul_f32 v[34:35], v[34:35], v[184:185]
	v_pk_mul_f32 v[32:33], v[32:33], v[182:183]
	v_pk_mul_f32 v[28:29], v[28:29], v[114:115]
	v_pk_mul_f32 v[24:25], v[24:25], v[174:175]
	v_pk_mul_f32 v[20:21], v[20:21], v[178:179]
	v_pk_mul_f32 v[30:31], v[30:31], v[116:117]
	v_pk_mul_f32 v[26:27], v[26:27], v[176:177]
	v_pk_mul_f32 v[22:23], v[22:23], v[180:181]
	v_pk_mul_f32 v[18:19], v[18:19], v[184:185]
	v_pk_mul_f32 v[16:17], v[16:17], v[182:183]
	v_pk_mul_f32 v[12:13], v[12:13], v[114:115]
	v_pk_mul_f32 v[8:9], v[8:9], v[174:175]
	v_pk_mul_f32 v[4:5], v[4:5], v[178:179]
	v_pk_mul_f32 v[14:15], v[14:15], v[116:117]
	v_pk_mul_f32 v[10:11], v[10:11], v[176:177]
	v_pk_mul_f32 v[6:7], v[6:7], v[180:181]
	v_pk_mul_f32 v[2:3], v[2:3], v[184:185]
	v_pk_mul_f32 v[0:1], v[0:1], v[182:183]
	ds_read_b128 v[114:117], v242 offset:128
	s_waitcnt lgkmcnt(0)
	v_pk_mul_f32 v[64:65], v[64:65], v[114:115]
	v_pk_mul_f32 v[66:67], v[66:67], v[116:117]

; __device__ __forceinline__ void qkt8(f32x16& p0, f32x16& p1, const char* Ks, const i32x8* qf, int r32, int hi) {
;   p0 = f32x16{}; p1 = f32x16{};
;   const char* kb = Ks + r32 * K8ROW + hi * 32;
;   i32x8 a0 = ld32B(kb), a1 = ld32B(kb + 32 * K8ROW);
;   i32x8 b0 = ld32B(kb + 64), b1 = ld32B(kb + 32 * K8ROW + 64);
;   p0 = mfma8(a0, qf[0], p0); p1 = mfma8(a1, qf[0], p1);
;   a0 = ld32B(kb + 128); a1 = ld32B(kb + 32 * K8ROW + 128);
;   p0 = mfma8(b0, qf[1], p0); p1 = mfma8(b1, qf[1], p1);
;   p0 = mfma8(a0, qf[2], p0); p1 = mfma8(a1, qf[2], p1);
; }
; __device__ __forceinline__ void pv8(f32x16* o, f32x16& lacc, const char* Vs, i32x8 pf, int r32, int hi) {
;   const char* vb = Vs + r32 * V8ROW + hi * 32;
; #pragma unroll
;   for (int d0 = 0; d0 < 4; ++d0) o[d0] = mfma8(pf, ld32B(vb + d0 * 32 * V8ROW), o[d0]);
;   const int one4 = 0x38383838;
;   lacc = mfma8(pf, i32x8{one4, one4, one4, one4, one4, one4, one4, one4}, lacc);
; }
; __device__ __forceinline__ void partialSM8(f32x16& p0, f32x16& p1, float& m_reg, float& mn, float& alpha) {
;   float pmax = p0[0];
; #pragma unroll
;   for (int r = 1; r < 16; ++r) pmax = fmaxf(pmax, p0[r]);
; #pragma unroll
;   for (int r = 0; r < 16; ++r) pmax = fmaxf(pmax, p1[r]);
;   { auto rr = __builtin_amdgcn_permlane32_swap(__float_as_uint(pmax), __float_as_uint(pmax), false, false);
;     pmax = fmaxf(__uint_as_float(rr[0]), __uint_as_float(rr[1])); }
;   if (__builtin_expect(__all(pmax - m_reg <= THR8 * 8.f * 1.4426950408889634f), 1)) { mn = m_reg; alpha = 1.f; }
;   else { mn = fmaxf(m_reg, pmax); alpha = __builtin_amdgcn_exp2f((m_reg - mn) * 0.125f); m_reg = mn; }
;   const float mn8 = (P8SHIFT + 7.f - 0.0436f) * 8.f + 0.5f - mn;
; #pragma unroll
;   for (int r = 0; r < 16; ++r) p0[r] += mn8;
; #pragma unroll
;   for (int r = 0; r < 16; ++r) p1[r] += mn8;
; }
; __device__ __forceinline__ unsigned pk4u8(float a, float b, float c, float d) {
;   unsigned w = __builtin_amdgcn_cvt_pk_u8_f32(a, 0u, 0u); w = __builtin_amdgcn_cvt_pk_u8_f32(b, 1u, w);
;   w = __builtin_amdgcn_cvt_pk_u8_f32(c, 2u, w); return __builtin_amdgcn_cvt_pk_u8_f32(d, 3u, w);
; }
; __device__ __forceinline__ void finishSM8(f32x16& p0, f32x16& p1, i32x8& pf) {
; #pragma unroll
;   for (int w = 0; w < 4; ++w) { pf[w] = (int)pk4u8(p0[4 * w], p0[4 * w + 1], p0[4 * w + 2], p0[4 * w + 3]);
.LBB0_924:
	v_cndmask_b32_e64 v168, v172, v216, s[10:11]
	v_sub_f32_e32 v113, 0x42c04d6a, v168
	s_add_i32 s2, s22, 1
	v_add_f32_e32 v169, v102, v113
	s_and_b32 s2, s2, 3
	v_add_f32_e32 v114, v96, v113
	v_add_f32_e32 v115, v97, v113
	v_add_f32_e32 v116, v98, v113
	v_add_f32_e32 v117, v99, v113
	v_add_f32_e32 v118, v100, v113
	v_add_f32_e32 v119, v101, v113
	v_add_f32_e32 v186, v103, v113
	v_add_f32_e32 v187, v104, v113
	v_add_f32_e32 v188, v105, v113
	v_add_f32_e32 v189, v106, v113
	v_add_f32_e32 v190, v107, v113
	v_add_f32_e32 v191, v108, v113
	v_add_f32_e32 v194, v109, v113
	v_add_f32_e32 v195, v110, v113
	v_add_f32_e32 v196, v111, v113
	v_add_f32_e32 v197, v80, v113
	v_add_f32_e32 v198, v81, v113
	v_add_f32_e32 v199, v82, v113
	v_add_f32_e32 v202, v83, v113
	v_add_f32_e32 v203, v84, v113
	v_add_f32_e32 v204, v85, v113
	v_add_f32_e32 v205, v86, v113
	v_add_f32_e32 v207, v87, v113
	v_add_f32_e32 v216, v88, v113
	v_add_f32_e32 v226, v89, v113
	v_add_f32_e32 v227, v90, v113
	v_add_f32_e32 v228, v91, v113
	v_add_f32_e32 v229, v92, v113
	v_add_f32_e32 v230, v93, v113
	v_add_f32_e32 v231, v94, v113
	v_add_f32_e32 v113, v95, v113
	s_mulk_i32 s2, 0x3400
	v_add_u32_e32 v222, s2, v214
	ds_read_b128 v[80:83], v222 offset:51200
	ds_read_b128 v[84:87], v222 offset:51216
	v_cvt_pk_u8_f32 v114, v114, 0, 0
	v_cvt_pk_u8_f32 v114, v115, 1, v114
	v_cvt_pk_u8_f32 v114, v116, 2, v114
	s_waitcnt lgkmcnt(0)
	v_mfma_scale_f32_32x32x64_f8f6f4 v[96:111], v[80:87], v[120:127], 0, v193, v193 op_sel_hi:[0,0,0]
	ds_read_b128 v[80:83], v222 offset:57856
	ds_read_b128 v[84:87], v222 offset:57872
	ds_read_b128 v[170:173], v222 offset:51264
	ds_read_b128 v[174:177], v222 offset:51280
	s_waitcnt lgkmcnt(2)
	v_mfma_scale_f32_32x32x64_f8f6f4 v[80:95], v[80:87], v[120:127], 0, v193, v193 op_sel_hi:[0,0,0]
	s_waitcnt lgkmcnt(0)
	v_mfma_scale_f32_32x32x64_f8f6f4 v[96:111], v[170:177], v[128:135], v[96:111], v193, v193 op_sel_hi:[0,0,0]
	ds_read_b128 v[170:173], v222 offset:57920
	ds_read_b128 v[174:177], v222 offset:57936
	ds_read_b128 v[178:181], v222 offset:51328
	ds_read_b128 v[182:185], v222 offset:51344
	ds_read_b128 v[218:221], v222 offset:57984
	ds_read_b128 v[222:225], v222 offset:58000
	s_waitcnt lgkmcnt(4)
	v_mfma_scale_f32_32x32x64_f8f6f4 v[80:95], v[170:177], v[128:135], v[80:95], v193, v193 op_sel_hi:[0,0,0]
	v_cvt_pk_u8_f32 v172, v117, 3, v114
	v_cvt_pk_u8_f32 v114, v197, 0, 0
	v_cvt_pk_u8_f32 v114, v198, 1, v114
	v_cvt_pk_u8_f32 v114, v199, 2, v114
	v_cvt_pk_u8_f32 v176, v202, 3, v114
	v_cvt_pk_u8_f32 v114, v118, 0, 0
	v_cvt_pk_u8_f32 v114, v119, 1, v114
	v_cvt_pk_u8_f32 v114, v169, 2, v114
	v_cvt_pk_u8_f32 v173, v186, 3, v114
	v_cvt_pk_u8_f32 v114, v203, 0, 0
	v_cvt_pk_u8_f32 v114, v204, 1, v114
	v_cvt_pk_u8_f32 v114, v205, 2, v114
	v_cvt_pk_u8_f32 v177, v207, 3, v114
	v_cvt_pk_u8_f32 v114, v187, 0, 0
	v_cvt_pk_u8_f32 v114, v188, 1, v114
	s_waitcnt lgkmcnt(2)
	v_mfma_scale_f32_32x32x64_f8f6f4 v[96:111], v[178:185], v[136:143], v[96:111], v193, v193 op_sel_hi:[0,0,0]
	v_cvt_pk_u8_f32 v114, v189, 2, v114
	v_cvt_pk_u8_f32 v174, v190, 3, v114
	v_cvt_pk_u8_f32 v114, v216, 0, 0
	v_cvt_pk_u8_f32 v114, v226, 1, v114
	v_cvt_pk_u8_f32 v114, v227, 2, v114
	v_cvt_pk_u8_f32 v178, v228, 3, v114
	v_cvt_pk_u8_f32 v114, v191, 0, 0
	v_cvt_pk_u8_f32 v114, v194, 1, v114
	v_cvt_pk_u8_f32 v114, v195, 2, v114
	v_cvt_pk_u8_f32 v175, v196, 3, v114
	v_cvt_pk_u8_f32 v114, v229, 0, 0
	v_cvt_pk_u8_f32 v114, v230, 1, v114
	v_cvt_pk_u8_f32 v114, v231, 2, v114
	v_cvt_pk_u8_f32 v179, v113, 3, v114
	s_waitcnt lgkmcnt(0)
	v_mfma_scale_f32_32x32x64_f8f6f4 v[80:95], v[218:225], v[136:143], v[80:95], v193, v193 op_sel_hi:[0,0,0]
	s_mul_i32 s2, s16, 0x2800
	s_addk_i32 s2, 0xd800
	s_cmp_lg_u32 s16, 0
	s_cselect_b32 s2, s2, 0xa000
	v_add_u32_e32 v113, s2, v217
	ds_read_b128 v[180:183], v113
	ds_read_b128 v[184:187], v113 offset:16
	v_max_f32_e32 v169, v97, v97
	v_max_f32_e32 v170, v96, v96
	v_max_f32_e32 v169, v170, v169
	v_max3_f32 v169, v169, v98, v99
	v_max3_f32 v169, v169, v100, v101
	s_waitcnt lgkmcnt(0)
	v_mfma_scale_f32_32x32x64_f8f6f4 v[48:63], v[172:179], v[180:187], v[48:63], v193, v193 op_sel_hi:[0,0,0]
	ds_read_b128 v[180:183], v113 offset:2560
	ds_read_b128 v[184:187], v113 offset:2576
	v_max3_f32 v169, v169, v102, v103
	v_max3_f32 v169, v169, v104, v105
	v_max3_f32 v169, v169, v106, v107
	v_max3_f32 v169, v169, v108, v109
	v_max3_f32 v169, v169, v110, v111
	v_max3_f32 v169, v169, v80, v81
	v_max3_f32 v169, v169, v82, v83
	v_max3_f32 v169, v169, v84, v85
	v_max3_f32 v169, v169, v86, v87
	s_waitcnt lgkmcnt(0)
	v_mfma_scale_f32_32x32x64_f8f6f4 v[32:47], v[172:179], v[180:187], v[32:47], v193, v193 op_sel_hi:[0,0,0]
	ds_read_b128 v[180:183], v113 offset:5120
	ds_read_b128 v[184:187], v113 offset:5136
	ds_read_b128 v[218:221], v113 offset:7680
	ds_read_b128 v[222:225], v113 offset:7696
	v_max3_f32 v169, v169, v88, v89
	v_max3_f32 v169, v169, v90, v91
	v_max3_f32 v169, v169, v92, v93
	v_max3_f32 v169, v169, v94, v95
	v_mov_b32_e32 v170, v169
	s_nop 1
	v_permlane32_swap_b32_e32 v169, v170
	v_max_f32_e32 v169, v169, v170
	v_sub_f32_e32 v170, v169, v168
	v_cmp_ge_f32_e32 vcc, s61, v170
	s_waitcnt lgkmcnt(2)
	v_mfma_scale_f32_32x32x64_f8f6f4 v[16:31], v[172:179], v[180:187], v[16:31], v193, v193 op_sel_hi:[0,0,0]
	s_cmp_eq_u64 vcc, exec
	s_cselect_b64 s[10:11], -1, 0
	s_waitcnt lgkmcnt(0)
	v_mfma_scale_f32_32x32x64_f8f6f4 v[0:15], v[172:179], v[218:225], v[0:15], v193, v193 op_sel_hi:[0,0,0]
	v_mfma_scale_f32_16x16x128_f8f6f4 v[64:67], v[172:179], v[244:251], v[64:67], v193, v193 op_sel_hi:[0,0,0]
	s_cbranch_scc1 .LBB0_928
; __device__ __forceinline__ void partialSM8(f32x16& p0, f32x16& p1, float& m_reg, float& mn, float& alpha) {
;     ...
;   if (__builtin_expect(__all(pmax - m_reg <= THR8 * 8.f * 1.4426950408889634f), 1)) { mn = m_reg; alpha = 1.f; }
;   else { mn = fmaxf(m_reg, pmax); alpha = __builtin_amdgcn_exp2f((m_reg - mn) * 0.125f); m_reg = mn; }
	v_max_f32_e32 v169, v168, v169
	v_sub_f32_e32 v171, v168, v169
	v_mul_f32_e32 v171, 0x3e000000, v171
	v_exp_f32_e32 v171, v171
	s_nop 0
	v_mov_b32_e32 v170, v171
	v_cmp_gt_f32_e32 vcc, 1.0, v170
	s_cbranch_vccz .LBB0_928
	s_and_saveexec_b64 s[14:15], s[8:9]
	ds_write_b32 v215, v170 offset:128
	s_or_b64 exec, exec, s[14:15]
	s_waitcnt lgkmcnt(0)
	v_add_u32_e32 v113, v159, v213
	ds_read_b128 v[114:117], v113 offset:224
	ds_read_b128 v[170:173], v113 offset:192
	ds_read_b128 v[174:177], v113 offset:160
	ds_read_b128 v[178:181], v113 offset:128
	s_waitcnt lgkmcnt(3)
	v_pk_mul_f32 v[60:61], v[60:61], v[114:115]
	s_waitcnt lgkmcnt(2)
	v_pk_mul_f32 v[56:57], v[56:57], v[170:171]
	s_waitcnt lgkmcnt(1)
	v_pk_mul_f32 v[52:53], v[52:53], v[174:175]
	v_pk_mul_f32 v[62:63], v[62:63], v[116:117]
	v_pk_mul_f32 v[58:59], v[58:59], v[172:173]
	v_pk_mul_f32 v[54:55], v[54:55], v[176:177]
	s_waitcnt lgkmcnt(0)
	v_pk_mul_f32 v[50:51], v[50:51], v[180:181]
	v_pk_mul_f32 v[48:49], v[48:49], v[178:179]
	v_pk_mul_f32 v[44:45], v[44:45], v[114:115]
	v_pk_mul_f32 v[40:41], v[40:41], v[170:171]
	v_pk_mul_f32 v[36:37], v[36:37], v[174:175]
	v_pk_mul_f32 v[46:47], v[46:47], v[116:117]
	v_pk_mul_f32 v[42:43], v[42:43], v[172:173]
	v_pk_mul_f32 v[38:39], v[38:39], v[176:177]
	v_pk_mul_f32 v[34:35], v[34:35], v[180:181]
	v_pk_mul_f32 v[32:33], v[32:33], v[178:179]
	v_pk_mul_f32 v[28:29], v[28:29], v[114:115]
	v_pk_mul_f32 v[24:25], v[24:25], v[170:171]
	v_pk_mul_f32 v[20:21], v[20:21], v[174:175]
	v_pk_mul_f32 v[30:31], v[30:31], v[116:117]
	v_pk_mul_f32 v[26:27], v[26:27], v[172:173]
	v_pk_mul_f32 v[22:23], v[22:23], v[176:177]
	v_pk_mul_f32 v[18:19], v[18:19], v[180:181]
	v_pk_mul_f32 v[16:17], v[16:17], v[178:179]
	v_pk_mul_f32 v[12:13], v[12:13], v[114:115]
	v_pk_mul_f32 v[8:9], v[8:9], v[170:171]
	v_pk_mul_f32 v[4:5], v[4:5], v[174:175]
	v_pk_mul_f32 v[14:15], v[14:15], v[116:117]
	v_pk_mul_f32 v[10:11], v[10:11], v[172:173]
	v_pk_mul_f32 v[6:7], v[6:7], v[176:177]
	v_pk_mul_f32 v[2:3], v[2:3], v[180:181]
	v_pk_mul_f32 v[0:1], v[0:1], v[178:179]
	ds_read_b128 v[114:117], v242 offset:128
	s_waitcnt lgkmcnt(0)
	v_pk_mul_f32 v[64:65], v[64:65], v[114:115]
	v_pk_mul_f32 v[66:67], v[66:67], v[116:117]
